# HGRN step B/C: LDS fragment reads batched ahead of their MFMAs with counted lgkmcnt (QT.KT, QH.ST, PP.VT, KD.VT chains), VT reads hoisted above barrier 3
# baseline (speedup 1.0000x reference)
; #define LAS __attribute__((address_space(3)))
; __device__ __forceinline__ void hgrn_item(LAS unsigned char* lds, int item, const bf16_t* QS, const float* LF, const bf16_t* KK, const bf16_t* VV, bf16_t* YAB) {
;     ...
;                 for (int j = 0; j < 4; ++j) { const int t = ti * 16 + quad * 4 + j, s = si * 16 + l15; PP[t * 72 + s] = f2bf((s <= t) ? a[j] : 0.f); }
;             }
; #pragma unroll
;             for (int ks = 0; ks < 4; ++ks) {
;                 const bf16x8 af = *(const LAS bf16x8*)(QH + (tt * 16 + l15) * 136 + ks * 32 + quad * 8);
; #pragma unroll
;                 for (int v2 = 0; v2 < 2; ++v2) {
;                     const bf16x8 bfr = *(const LAS bf16x8*)(ST + ((vt0 + v2) * 16 + l15) * 136 + ks * 32 + quad * 8);
;                     acc_o[v2] = MFMA16(af, bfr, acc_o[v2]);
;                 }
;             }
;         }
;         __syncthreads();
; #pragma unroll
;         for (int ks = 0; ks < 2; ++ks) {
;             const bf16x8 af = *(const LAS bf16x8*)(PP + (tt * 16 + l15) * 72 + ks * 32 + quad * 8);
; #pragma unroll
;             for (int v2 = 0; v2 < 2; ++v2) {
;                 const bf16x8 bfr = *(const LAS bf16x8*)(VT + ((vt0 + v2) * 16 + l15) * 72 + ks * 32 + quad * 8);
;                 acc_o[v2] = MFMA16(af, bfr, acc_o[v2]);
;             }
;         }
; #pragma unroll
;         for (int v2 = 0; v2 < 2; ++v2)
; #pragma unroll
;             for (int j = 0; j < 4; ++j) YAB[(row0 + (size_t)c * 64 + tt * 16 + quad * 4 + j) * D + h * 128 + vh * 64 + (vt0 + v2) * 16 + l15] = f2bf(acc_o[v2][j]);
;         {
;             const f32x4 dv = *(const LAS f32x4*)(DD + wid * 16 + quad * 4);
; #pragma unroll
;             for (int v4 = 0; v4 < 4; ++v4) S[v4] *= dv;
; #pragma unroll
;             for (int ks = 0; ks < 2; ++ks) {
;                 const bf16x8 af = *(const LAS bf16x8*)(KD + (wid * 16 + l15) * 72 + ks * 32 + quad * 8);
; #pragma unroll
;                 for (int v4 = 0; v4 < 4; ++v4) {
;                     const bf16x8 bfr = *(const LAS bf16x8*)(VT + (v4 * 16 + l15) * 72 + ks * 32 + quad * 8);
;                     S[v4] = MFMA16(af, bfr, S[v4]);
;                 }
;             }
; #pragma unroll
;             for (int v4 = 0; v4 < 4; ++v4) { u32x2 w; w.x = cvt_pk_bf16(S[v4][0], S[v4][1]); w.y = cvt_pk_bf16(S[v4][2], S[v4][3]); *(LAS u32x2*)(ST + (v4 * 16 + l15) * 136 + wid * 16 + quad * 4) = w; }
.LBB0_692:
	s_or_b64 exec, exec, s[38:39]
	s_nop 5
	v_cvt_pk_bf16_f32 v20, v20, s0
	v_cndmask_b32_e64 v20, v20, 0, s[92:93]
	ds_write_b16 v138, v20
	v_cvt_pk_bf16_f32 v20, v21, s0
	v_cndmask_b32_e64 v20, v20, 0, s[28:29]
	ds_write_b16 v139, v20
	v_cvt_pk_bf16_f32 v20, v22, s0
	v_cndmask_b32_e64 v20, v20, 0, s[30:31]
	ds_write_b16 v140, v20
	v_cvt_pk_bf16_f32 v20, v23, s0
	v_cndmask_b32_e64 v20, v20, 0, s[34:35]
	ds_write_b16 v141, v20
	ds_read_b128 v[20:23], v129 offset:34816
	v_add_u32_e32 v24, v130, v137
	ds_read_b128 v[210:213], v24
	ds_read_b128 v[214:217], v155
	ds_read_b128 v[218:221], v129 offset:34880
	ds_read_b128 v[222:225], v24 offset:64
	ds_read_b128 v[226:229], v155 offset:64
	s_mov_b32 s33, 0x15e00000
	v_lshl_add_u64 v[98:99], v[98:99], 0, s[54:55]
	s_waitcnt lgkmcnt(4)
	v_mfma_f32_16x16x32_bf16 v[210:213], v[20:23], v[210:213], 0
	v_lshl_add_u64 v[100:101], v[100:101], 0, s[54:55]
	v_lshl_add_u64 v[102:103], v[102:103], 0, s[52:53]
	s_waitcnt lgkmcnt(3)
	v_mfma_f32_16x16x32_bf16 v[20:23], v[20:23], v[214:217], 0
	ds_read_b128 v[214:217], v129 offset:34944
	s_waitcnt lgkmcnt(2)
	v_mfma_f32_16x16x32_bf16 v[210:213], v[218:221], v[222:225], v[210:213]
	ds_read_b128 v[222:225], v24 offset:128
	s_waitcnt lgkmcnt(2)
	v_mfma_f32_16x16x32_bf16 v[20:23], v[218:221], v[226:229], v[20:23]
	ds_read_b128 v[226:229], v155 offset:128
	ds_read_b128 v[218:221], v129 offset:35008
	s_waitcnt lgkmcnt(2)
	v_mfma_f32_16x16x32_bf16 v[210:213], v[214:217], v[222:225], v[210:213]
	ds_read_b128 v[222:225], v24 offset:192
	v_lshl_add_u64 v[24:25], v[94:95], 0, s[0:1]
	s_waitcnt lgkmcnt(2)
	v_mfma_f32_16x16x32_bf16 v[20:23], v[214:217], v[226:229], v[20:23]
	ds_read_b128 v[226:229], v155 offset:192
	ds_read_b128 v[214:217], v156
	s_waitcnt lgkmcnt(2)
	v_mfma_f32_16x16x32_bf16 v[210:213], v[218:221], v[222:225], v[210:213]
	ds_read_b128 v[222:225], v157
	s_waitcnt lgkmcnt(2)
	s_barrier
	v_mfma_f32_16x16x32_bf16 v[20:23], v[218:221], v[226:229], v[20:23]
	ds_read_b128 v[218:221], v131
	ds_read_b128 v[226:229], v131 offset:64
	s_waitcnt lgkmcnt(1)
	v_mfma_f32_16x16x32_bf16 v[210:213], v[218:221], v[214:217], v[210:213]
	ds_read_b128 v[214:217], v156 offset:64
	v_mfma_f32_16x16x32_bf16 v[20:23], v[218:221], v[222:225], v[20:23]
	ds_read_b128 v[222:225], v157 offset:64
	s_waitcnt lgkmcnt(1)
	v_mfma_f32_16x16x32_bf16 v[210:213], v[226:229], v[214:217], v[210:213]
	s_waitcnt lgkmcnt(0)
	v_mfma_f32_16x16x32_bf16 v[20:23], v[226:229], v[222:225], v[20:23]
	v_lshl_add_u64 v[214:215], s[24:25], 0, v[96:97]
	v_add_co_u32_e32 v214, vcc, s33, v214
	s_nop 4
	v_cvt_pk_bf16_f32 v26, v210, s0
	v_addc_co_u32_e32 v215, vcc, 0, v215, vcc
	global_store_short v[214:215], v26, off
	v_cvt_pk_bf16_f32 v26, v211, s0
	v_or_b32_e32 v210, 0x1000, v24
	v_mov_b32_e32 v211, v25
	v_lshl_add_u64 v[210:211], v[92:93], 0, v[210:211]
	v_or_b32_e32 v216, 0x2000, v24
	v_mov_b32_e32 v217, v25
	global_store_short v[210:211], v26, off
	v_cvt_pk_bf16_f32 v26, v212, s0
	v_lshl_add_u64 v[216:217], v[92:93], 0, v[216:217]
	v_or_b32_e32 v24, 0x3000, v24
	global_store_short v[216:217], v26, off
	v_cvt_pk_bf16_f32 v26, v213, s0
	v_lshl_add_u64 v[24:25], v[92:93], 0, v[24:25]
	v_cvt_pk_bf16_f32 v20, v20, s0
	global_store_short v[24:25], v26, off
	global_store_short v[214:215], v20, off offset:32
	v_cvt_pk_bf16_f32 v20, v21, s0
	global_store_short v[210:211], v20, off offset:32
	v_cvt_pk_bf16_f32 v20, v22, s0
	global_store_short v[216:217], v20, off offset:32
	v_cvt_pk_bf16_f32 v20, v23, s0
	global_store_short v[24:25], v20, off offset:32
	ds_read_b128 v[20:23], v132
	ds_read_b128 v[226:229], v133 offset:52224
	ds_read_b128 v[210:213], v158
	ds_read_b128 v[214:217], v158 offset:2304
	ds_read_b128 v[218:221], v158 offset:4608
	ds_read_b128 v[222:225], v158 offset:6912
	s_add_u32 s0, s0, 0x40000
	s_addc_u32 s1, s1, 0
	v_lshl_add_u64 v[96:97], v[96:97], 0, s[52:53]
	s_cmp_lg_u32 s0, 0x1000000
	s_waitcnt lgkmcnt(5)
	v_pk_mul_f32 v[2:3], v[2:3], v[22:23]
	v_pk_mul_f32 v[0:1], v[0:1], v[20:21]
	v_pk_mul_f32 v[6:7], v[6:7], v[22:23]
	v_pk_mul_f32 v[4:5], v[4:5], v[20:21]
	v_pk_mul_f32 v[14:15], v[14:15], v[22:23]
	v_pk_mul_f32 v[12:13], v[12:13], v[20:21]
	v_pk_mul_f32 v[18:19], v[18:19], v[22:23]
	v_pk_mul_f32 v[16:17], v[16:17], v[20:21]
	ds_read_b128 v[20:23], v133 offset:52288
	s_waitcnt lgkmcnt(4)
	v_mfma_f32_16x16x32_bf16 v[0:3], v[226:229], v[210:213], v[0:3]
	ds_read_b128 v[210:213], v158 offset:64
	s_waitcnt lgkmcnt(4)
	v_mfma_f32_16x16x32_bf16 v[4:7], v[226:229], v[214:217], v[4:7]
	ds_read_b128 v[214:217], v158 offset:2368
	s_waitcnt lgkmcnt(4)
	v_mfma_f32_16x16x32_bf16 v[12:15], v[226:229], v[218:221], v[12:15]
	ds_read_b128 v[218:221], v158 offset:4672
	s_waitcnt lgkmcnt(4)
	v_mfma_f32_16x16x32_bf16 v[16:19], v[226:229], v[222:225], v[16:19]
	ds_read_b128 v[222:225], v158 offset:6976
	s_waitcnt lgkmcnt(3)
	v_mfma_f32_16x16x32_bf16 v[0:3], v[20:23], v[210:213], v[0:3]
	s_waitcnt lgkmcnt(2)
	v_mfma_f32_16x16x32_bf16 v[4:7], v[20:23], v[214:217], v[4:7]
	s_waitcnt lgkmcnt(1)
	v_mfma_f32_16x16x32_bf16 v[12:15], v[20:23], v[218:221], v[12:15]
	s_waitcnt lgkmcnt(0)
	v_mfma_f32_16x16x32_bf16 v[16:19], v[20:23], v[222:225], v[16:19]
	s_nop 2
	v_cvt_pk_bf16_f32 v20, v0, v1
	v_cvt_pk_bf16_f32 v21, v2, v3
	ds_write_b64 v159, v[20:21]
	v_cvt_pk_bf16_f32 v20, v4, v5
	v_cvt_pk_bf16_f32 v21, v6, v7
	ds_write_b64 v159, v[20:21] offset:4352
	v_cvt_pk_bf16_f32 v20, v12, v13
	v_cvt_pk_bf16_f32 v21, v14, v15
	ds_write_b64 v159, v[20:21] offset:8704
	v_cvt_pk_bf16_f32 v20, v16, v17
	v_cvt_pk_bf16_f32 v21, v18, v19
	ds_write_b64 v159, v[20:21] offset:13056
	s_waitcnt vmcnt(8)
	v_perm_b32 v81, v232, v81, s47
	v_perm_b32 v91, v233, v91, s47
	v_perm_b32 v204, v234, v204, s47
	v_perm_b32 v205, v235, v205, s47
	v_perm_b32 v206, v236, v206, s47
	v_perm_b32 v207, v237, v207, s47
	v_perm_b32 v208, v238, v208, s47
	v_perm_b32 v209, v239, v209, s47
	v_lshl_or_b32 v8, v240, 16, v8
	v_lshl_or_b32 v9, v241, 16, v9
	v_lshl_or_b32 v10, v242, 16, v10
	v_lshl_or_b32 v11, v243, 16, v11
	s_cbranch_scc0 .LBB0_630

; #define LAS __attribute__((address_space(3)))
; __device__ __forceinline__ bf16_t f2bf(float f) { return (bf16_t)(cvt_pk_bf16(f, 0.f) & 0xffffu); }
; #define MFMA16(a, b, c) __builtin_amdgcn_mfma_f32_16x16x32_bf16((a), (b), (c), 0, 0, 0)
; __device__ __forceinline__ void hgrn_item(LAS unsigned char* lds, int item, const bf16_t* QS, const float* LF, const bf16_t* KK, const bf16_t* VV, bf16_t* YAB) {
;     ...
;             for (int q2 = 0; q2 < 2; ++q2) {
;                 const int si = (wid & 1) * 2 + q2;
;                 f32x4 a = (f32x4){0.f, 0.f, 0.f, 0.f};
;                 if (si <= ti) {
; #pragma unroll
;                     for (int ks = 0; ks < 4; ++ks) {
;                         const bf16x8 af = *(const LAS bf16x8*)(QT + (ti * 16 + l15) * 136 + ks * 32 + quad * 8);
;                         const bf16x8 bfr = *(const LAS bf16x8*)(KT + (si * 16 + l15) * 136 + ks * 32 + quad * 8);
;                         a = MFMA16(af, bfr, a);
;                     }
;                 }
; #pragma unroll
;                 for (int j = 0; j < 4; ++j) { const int t = ti * 16 + quad * 4 + j, s = si * 16 + l15; PP[t * 72 + s] = f2bf((s <= t) ? a[j] : 0.f); }
;             }
.LBB0_705:
	v_mov_b32_e32 v20, 0
	v_add_u32_e32 v26, v45, v137
	v_mov_b32_e32 v22, 0
	v_mov_b32_e32 v23, 0
	v_mov_b32_e32 v24, 0
	v_mov_b32_e32 v25, 0
	s_and_saveexec_b64 s[38:39], s[56:57]
	s_cbranch_execz .LBB0_707
	ds_read_b128 v[22:25], v129
	ds_read_b128 v[210:213], v26 offset:17408
	ds_read_b128 v[214:217], v129 offset:64
	ds_read_b128 v[218:221], v26 offset:17472
	ds_read_b128 v[222:225], v129 offset:128
	ds_read_b128 v[226:229], v26 offset:17536
	s_waitcnt lgkmcnt(4)
	v_mfma_f32_16x16x32_bf16 v[22:25], v[22:25], v[210:213], 0
	ds_read_b128 v[210:213], v129 offset:192
	s_waitcnt lgkmcnt(3)
	v_mfma_f32_16x16x32_bf16 v[22:25], v[214:217], v[218:221], v[22:25]
	ds_read_b128 v[214:217], v26 offset:17600
	s_waitcnt lgkmcnt(2)
	v_mfma_f32_16x16x32_bf16 v[22:25], v[222:225], v[226:229], v[22:25]
	s_waitcnt lgkmcnt(0)
	v_mfma_f32_16x16x32_bf16 v[22:25], v[210:213], v[214:217], v[22:25]
.LBB0_707:
	s_or_b64 exec, exec, s[38:39]
	s_nop 6
	v_cvt_pk_bf16_f32 v21, v22, s0
	v_cndmask_b32_e64 v21, v21, 0, s[64:65]
	ds_write_b16 v154, v21
	v_cvt_pk_bf16_f32 v21, v23, s0
	v_cndmask_b32_e64 v21, v21, 0, s[42:43]
	ds_write_b16 v154, v21 offset:144
	v_cvt_pk_bf16_f32 v21, v24, s0
	v_cndmask_b32_e64 v21, v21, 0, s[44:45]
	ds_write_b16 v154, v21 offset:288
	v_cvt_pk_bf16_f32 v21, v25, s0
	v_cndmask_b32_e64 v21, v21, 0, s[36:37]
	ds_write_b16 v154, v21 offset:432
	v_mov_b32_e32 v21, 0
	v_mov_b32_e32 v22, 0
	v_mov_b32_e32 v23, 0
	s_and_saveexec_b64 s[38:39], s[48:49]
	s_cbranch_execz .LBB0_692
	ds_read_b128 v[20:23], v129
	ds_read_b128 v[210:213], v26 offset:21760
	ds_read_b128 v[214:217], v129 offset:64
	ds_read_b128 v[218:221], v26 offset:21824
	ds_read_b128 v[222:225], v129 offset:128
	ds_read_b128 v[226:229], v26 offset:21888
	s_waitcnt lgkmcnt(4)
	v_mfma_f32_16x16x32_bf16 v[20:23], v[20:23], v[210:213], 0
	ds_read_b128 v[210:213], v129 offset:192
	s_waitcnt lgkmcnt(3)
	v_mfma_f32_16x16x32_bf16 v[20:23], v[214:217], v[218:221], v[20:23]
	ds_read_b128 v[214:217], v26 offset:21952
	s_waitcnt lgkmcnt(2)
	v_mfma_f32_16x16x32_bf16 v[20:23], v[222:225], v[226:229], v[20:23]
	s_waitcnt lgkmcnt(0)
	v_mfma_f32_16x16x32_bf16 v[20:23], v[210:213], v[214:217], v[20:23]
	s_branch .LBB0_692
